# speedup vs baseline: 1.0095x; 1.0006x over previous
; #define LAS __attribute__((address_space(3)))
; __device__ __forceinline__ float ret_log_gamma(int h) { return log1pf(-exp2f(-5.0f - (float)h)); }
; template <bool DEC> __device__ __forceinline__ void stage_rot128(LAS bf16_t* dst, const bf16_t* proj, int col, int tok0, const float* cosT, const float* sinT, float sc_base, float lg, int tid) {
;     u32x4 r1[2], r2[2]; f32x4 cc[2][2], sn[2][2];
; #pragma unroll
;     for (int it = 0; it < 2; ++it) { const int e = tid + it * NTHR, j = e & 127, c = e >> 7, tok = tok0 + j; const bf16_t* rp = proj + (size_t)tok * LDP + col;
;         r1[it] = *(const u32x4*)(rp + 8 * c); r2[it] = *(const u32x4*)(rp + 64 + 8 * c);
;         cc[it][0] = *(const f32x4*)(cosT + tok * 64 + 8 * c); cc[it][1] = *(const f32x4*)(cosT + tok * 64 + 8 * c + 4); sn[it][0] = *(const f32x4*)(sinT + tok * 64 + 8 * c); sn[it][1] = *(const f32x4*)(sinT + tok * 64 + 8 * c + 4); }
; __device__ __forceinline__ void retc1_unit(LAS unsigned char* lds, const bf16_t* proj, const float* cosT, const float* sinT, bf16_t* KVT, int h, int n, int tid) {
;     LAS bf16_t* Ks = (LAS bf16_t*)(lds + C_T0); LAS bf16_t* Vs = (LAS bf16_t*)(lds + C_T1);
;     const float lg = ret_log_gamma(h);
;     stage_rot128<true>(Ks, proj, C_CK + h * 128, n * 128, cosT, sinT, 0.08838834764831845f, lg, tid);
;     stage_v128(Vs, proj, C_CV + h * 128, n * 128, tid);
.LBB0_278:
	s_ashr_i32 s9, s8, 31
	s_lshr_b32 s10, s9, 25
	s_add_i32 s14, s8, s10
	s_ashr_i32 s13, s14, 7
	v_cvt_f32_i32_e32 v0, s13
	v_sub_f32_e32 v0, 0xc0a00000, v0
	v_cmp_gt_f32_e32 vcc, s22, v0
	s_and_b64 s[10:11], vcc, exec
	s_cselect_b32 s10, 0xffffffc0, 0
	v_cndmask_b32_e32 v1, 0, v209, vcc
	v_add_f32_e32 v0, v0, v1
	v_exp_f32_e32 v0, v0
	s_mul_i32 s11, s13, 0xe2000000
	v_ldexp_f32 v23, v0, s10
	v_sub_f32_e32 v2, 1.0, v23
	v_add_f32_e32 v0, -1.0, v2
	v_sub_f32_e32 v1, v0, v2
	v_add_f32_e32 v1, 1.0, v1
	v_sub_f32_e64 v0, -v23, v0
	v_add_f32_e32 v3, v0, v1
	v_frexp_mant_f32_e32 v0, v2
	v_cmp_gt_f32_e32 vcc, s24, v0
	v_cvt_f64_f32_e32 v[0:1], v2
	v_frexp_exp_i32_f64_e32 v0, v[0:1]
	v_subbrev_co_u32_e32 v8, vcc, 0, v0, vcc
	v_sub_u32_e32 v0, 0, v8
	v_ldexp_f32 v1, v2, v0
	v_add_f32_e32 v2, -1.0, v1
	v_add_f32_e32 v4, 1.0, v1
	v_ldexp_f32 v0, v3, v0
	v_add_f32_e32 v3, 1.0, v2
	v_add_f32_e32 v5, -1.0, v4
	v_sub_f32_e32 v3, v1, v3
	v_sub_f32_e32 v1, v1, v5
	v_add_f32_e32 v3, v0, v3
	v_add_f32_e32 v0, v0, v1
	v_add_f32_e32 v9, v4, v0
	v_rcp_f32_e32 v11, v9
	v_sub_f32_e32 v1, v9, v4
	v_sub_f32_e32 v10, v0, v1
	v_add_f32_e32 v1, v2, v3
	v_mul_f32_e32 v13, v1, v11
	v_sub_f32_e32 v0, v1, v2
	v_mul_f32_e32 v2, v9, v13
	v_fma_f32 v4, v13, v9, -v2
	v_fmac_f32_e32 v4, v13, v10
	v_sub_f32_e32 v12, v3, v0
	v_add_f32_e32 v0, v2, v4
	v_sub_f32_e32 v3, v1, v0
	v_pk_add_f32 v[6:7], v[0:1], v[2:3] neg_lo:[0,1] neg_hi:[0,1]
	v_mov_b32_e32 v5, v0
	v_pk_add_f32 v[0:1], v[6:7], v[4:5] neg_lo:[0,1] neg_hi:[0,1]
	v_cmp_nlt_f32_e32 vcc, 1.0, v23
	v_add_f32_e32 v1, v12, v1
	v_add_f32_e32 v0, v0, v1
	v_add_f32_e32 v1, v3, v0
	v_mul_f32_e32 v12, v11, v1
	v_mul_f32_e32 v2, v9, v12
	v_fma_f32 v4, v12, v9, -v2
	v_fmac_f32_e32 v4, v12, v10
	v_sub_f32_e32 v3, v3, v1
	v_add_f32_e32 v9, v0, v3
	v_add_f32_e32 v0, v2, v4
	v_sub_f32_e32 v3, v1, v0
	v_pk_add_f32 v[6:7], v[0:1], v[2:3] neg_lo:[0,1] neg_hi:[0,1]
	v_mov_b32_e32 v5, v0
	v_pk_add_f32 v[0:1], v[6:7], v[4:5] neg_lo:[0,1] neg_hi:[0,1]
	s_and_b32 s10, s14, 0xffffff80
	v_add_f32_e32 v1, v9, v1
	v_add_f32_e32 v0, v0, v1
	v_add_f32_e32 v1, v13, v12
	v_add_f32_e32 v0, v3, v0
	v_sub_f32_e32 v2, v1, v13
	v_mul_f32_e32 v0, v11, v0
	v_sub_f32_e32 v2, v12, v2
	v_add_f32_e32 v2, v2, v0
	v_add_f32_e32 v4, v1, v2
	v_mul_f32_e32 v5, v4, v4
	v_fmamk_f32 v0, v5, 0x3e9b6dac, v206
	v_fmaak_f32 v171, v5, v0, 0x3f2aaada
	v_cvt_f32_i32_e32 v0, v8
	v_sub_f32_e32 v1, v4, v1
	v_sub_f32_e32 v1, v2, v1
	v_ldexp_f32 v6, v1, 1
	v_mul_f32_e32 v1, v4, v5
	v_ldexp_f32 v3, v4, 1
	v_pk_mul_f32 v[4:5], v[0:1], v[170:171]
	s_mov_b64 s[14:15], 0x2f00
	v_fma_f32 v2, v0, s20, -v4
	v_fmac_f32_e32 v2, 0xb102e308, v0
	v_pk_add_f32 v[0:1], v[4:5], v[2:3]
	s_nop 0
	v_sub_f32_e32 v3, v1, v3
	v_sub_f32_e32 v3, v5, v3
	v_add_f32_e32 v7, v6, v3
	v_mov_b32_e32 v6, v4
	v_pk_add_f32 v[4:5], v[0:1], v[4:5] neg_lo:[0,1] neg_hi:[0,1]
	v_pk_add_f32 v[8:9], v[0:1], v[6:7]
	v_mov_b32_e32 v3, v0
	v_mov_b32_e32 v5, v9
	v_pk_add_f32 v[10:11], v[2:3], v[4:5] neg_lo:[0,1] neg_hi:[0,1]
	v_pk_add_f32 v[2:3], v[2:3], v[4:5]
	v_mov_b32_e32 v14, v1
	v_pk_add_f32 v[4:5], v[2:3], v[0:1] op_sel:[1,0] op_sel_hi:[0,1] neg_lo:[0,1] neg_hi:[0,1]
	v_pk_add_f32 v[12:13], v[8:9], v[4:5] op_sel_hi:[1,0] neg_lo:[0,1] neg_hi:[0,1]
	v_mov_b32_e32 v8, v9
	v_mov_b32_e32 v9, v3
	v_mov_b32_e32 v15, v4
	v_pk_add_f32 v[4:5], v[8:9], v[14:15] neg_lo:[0,1] neg_hi:[0,1]
	v_mov_b32_e32 v6, v7
	v_mov_b32_e32 v7, v0
	v_pk_add_f32 v[0:1], v[6:7], v[4:5] neg_lo:[0,1] neg_hi:[0,1]
	v_mov_b32_e32 v12, v10
	v_pk_add_f32 v[4:5], v[12:13], v[0:1]
	v_mov_b32_e32 v11, v3
	v_pk_add_f32 v[6:7], v[4:5], v[4:5] op_sel:[0,1] op_sel_hi:[1,0]
	v_lshlrev_b64 v[14:15], 1, v[16:17]
	v_pk_add_f32 v[2:3], v[2:3], v[6:7] op_sel:[1,0] op_sel_hi:[0,1]
	v_mov_b32_e32 v5, v2
	v_pk_add_f32 v[8:9], v[4:5], v[10:11] neg_lo:[0,1] neg_hi:[0,1]
	v_mov_b32_e32 v1, v6
	v_sub_f32_e32 v3, v4, v8
	v_pk_add_f32 v[0:1], v[0:1], v[8:9] neg_lo:[0,1] neg_hi:[0,1]
	v_sub_f32_e32 v3, v10, v3
	v_add_f32_e32 v0, v0, v3
	v_add_f32_e32 v0, v0, v1
	v_add_f32_e32 v0, v2, v0
	v_cndmask_b32_e32 v0, v210, v0, vcc
	v_cmp_neq_f32_e32 vcc, 1.0, v23
	s_nop 1
	v_cndmask_b32_e32 v0, v211, v0, vcc
	v_cmp_gt_f32_e32 vcc, s25, v23
	s_nop 1
	v_cndmask_b32_e64 v8, v0, -v23, vcc
	v_add_u32_e32 v0, s11, v35
	v_ashrrev_i32_e32 v1, 31, v0
	s_ashr_i32 s11, s10, 31
	v_lshl_add_u64 v[0:1], s[40:41], 0, v[0:1]
	s_lshl_b64 s[10:11], s[10:11], 1
	v_lshl_add_u64 v[0:1], v[0:1], 0, s[10:11]
	v_lshl_add_u64 v[4:5], v[0:1], 0, s[14:15]
	s_mov_b64 s[14:15], 0x2f80
	v_lshl_add_u64 v[6:7], v[0:1], 0, s[14:15]
	s_lshl_b32 s14, s13, 20
	v_subrev_u32_e32 v0, s14, v36
	v_ashrrev_i32_e32 v1, 31, v0
	v_lshlrev_b64 v[0:1], 2, v[0:1]
	v_lshl_add_u64 v[10:11], v[4:5], 0, v[14:15]
	v_lshl_add_u64 v[14:15], v[6:7], 0, v[14:15]
	v_lshl_add_u64 v[2:3], s[4:5], 0, v[0:1]
	v_lshl_add_u64 v[0:1], s[6:7], 0, v[0:1]
	global_load_dwordx4 v[10:13], v[10:11], off
	v_mul_f32_e32 v8, v8, v28
	global_load_dwordx4 v[42:45], v[14:15], off
	v_lshlrev_b64 v[14:15], 2, v[16:17]
	v_lshl_add_u64 v[24:25], v[2:3], 0, v[14:15]
	v_lshl_add_u64 v[14:15], v[0:1], 0, v[14:15]
	global_load_dwordx4 v[46:49], v[24:25], off offset:16
	global_load_dwordx4 v[50:53], v[24:25], off
	global_load_dwordx4 v[54:57], v[14:15], off offset:16
	global_load_dwordx4 v[58:61], v[14:15], off
	v_lshlrev_b64 v[14:15], 1, v[18:19]
	v_lshl_add_u64 v[4:5], v[4:5], 0, v[14:15]
	global_load_dwordx4 v[62:65], v[4:5], off
	v_lshl_add_u64 v[4:5], v[6:7], 0, v[14:15]
	v_lshlrev_b64 v[14:15], 2, v[18:19]
	v_lshl_add_u64 v[2:3], v[2:3], 0, v[14:15]
	v_lshl_add_u64 v[14:15], v[0:1], 0, v[14:15]
	global_load_dwordx4 v[4:7], v[4:5], off
	s_nop 0
	global_load_dwordx4 v[66:69], v[2:3], off offset:16
	global_load_dwordx4 v[70:73], v[2:3], off
	s_nop 0
	global_load_dwordx4 v[0:3], v[14:15], off offset:16
	global_load_dwordx4 v[74:77], v[14:15], off
	v_mul_f32_e32 v8, 0x3fb8aa3b, v8
	v_exp_f32_e32 v8, v8
	s_add_u32 s10, s40, s10
	s_addc_u32 s11, s41, s11
	v_mov_b32_e32 v236, v22
	v_mov_b32_e32 v237, v32
	v_lshl_add_u64 v[236:237], s[10:11], 0, v[236:237]
	s_mov_b64 s[10:11], 0x3700
	v_lshl_add_u64 v[238:239], v[236:237], 0, s[10:11]
	s_lshl_b32 s10, s13, 14
	s_sub_i32 s13, s12, s10
	v_add_u32_e32 v236, s13, v26
	v_mad_i64_i32 v[240:241], s[10:11], v236, s23, v[238:239]
	v_add_u32_e32 v236, s13, v27
	global_load_dwordx4 v[220:223], v[240:241], off
	v_mad_i64_i32 v[240:241], s[10:11], v236, s23, v[238:239]
	v_add_u32_e32 v236, s13, v31
	global_load_dwordx4 v[224:227], v[240:241], off
	v_mad_i64_i32 v[240:241], s[10:11], v236, s23, v[238:239]
	v_add_u32_e32 v236, s13, v33
	global_load_dwordx4 v[228:231], v[240:241], off
	v_mad_i64_i32 v[240:241], s[10:11], v236, s23, v[238:239]
	global_load_dwordx4 v[232:235], v[240:241], off
	v_add_u32_e32 v36, s0, v36
	s_waitcnt vmcnt(15)
; #define LAS __attribute__((address_space(3)))
; __device__ __forceinline__ void lds_barrier() { asm volatile("s_waitcnt lgkmcnt(0)\n\ts_barrier" ::: "memory"); }
; __device__ __forceinline__ void unpack8(const u32x4 r, float (&v)[8]) { v[0] = bf_lo(r.x); v[1] = bf_hi(r.x); v[2] = bf_lo(r.y); v[3] = bf_hi(r.y); v[4] = bf_lo(r.z); v[5] = bf_hi(r.z); v[6] = bf_lo(r.w); v[7] = bf_hi(r.w); }
; __device__ __forceinline__ u32x4 pack8(const float (&v)[8]) { u32x4 w; w.x = cvt_pk_bf16(v[0], v[1]); w.y = cvt_pk_bf16(v[2], v[3]); w.z = cvt_pk_bf16(v[4], v[5]); w.w = cvt_pk_bf16(v[6], v[7]); return w; }
; template <bool DEC> __device__ __forceinline__ void stage_rot128(LAS bf16_t* dst, const bf16_t* proj, int col, int tok0, const float* cosT, const float* sinT, float sc_base, float lg, int tid) {
;     ...
; #pragma unroll
;     for (int it = 0; it < 2; ++it) { const int e = tid + it * NTHR, j = e & 127, c = e >> 7;
;         float x1[8], x2[8]; unpack8(r1[it], x1); unpack8(r2[it], x2);
;         float sc = sc_base; if (DEC) sc *= __expf(lg * (float)(127 - j));
;         float o1[8], o2[8];
; #pragma unroll
;         for (int t = 0; t < 8; ++t) { const float cs = cc[it][t >> 2][t & 3], sv = sn[it][t >> 2][t & 3]; o1[t] = (x1[t] * cs - x2[t] * sv) * sc; o2[t] = (x2[t] * cs + x1[t] * sv) * sc; }
;         *(LAS u32x4*)(dst + j * CP + 8 * c) = pack8(o1); *(LAS u32x4*)(dst + j * CP + 64 + 8 * c) = pack8(o2); }
; }
; __device__ __forceinline__ void stage_v128(LAS bf16_t* dst, const bf16_t* proj, int col, int tok0, int tid) {
;     u32x4 raw[4];
; #pragma unroll
;     for (int it = 0; it < 4; ++it) { const int e = tid + it * NTHR, j = e >> 4, c = e & 15; raw[it] = *(const u32x4*)(proj + (size_t)(tok0 + j) * LDP + col + 8 * c); }
; #pragma unroll
;     for (int it = 0; it < 4; ++it) { const int e = tid + it * NTHR, j = e >> 4, c = e & 15; *(LAS u32x4*)(dst + j * CP + 8 * c) = raw[it]; }
; }
; __device__ __forceinline__ void retc1_unit(LAS unsigned char* lds, const bf16_t* proj, const float* cosT, const float* sinT, bf16_t* KVT, int h, int n, int tid) {
;     LAS bf16_t* Ks = (LAS bf16_t*)(lds + C_T0); LAS bf16_t* Vs = (LAS bf16_t*)(lds + C_T1);
;     const float lg = ret_log_gamma(h);
;     stage_rot128<true>(Ks, proj, C_CK + h * 128, n * 128, cosT, sinT, 0.08838834764831845f, lg, tid);
;     stage_v128(Vs, proj, C_CV + h * 128, n * 128, tid);
;     lds_barrier();
	v_lshlrev_b32_e32 v14, 16, v10
	s_waitcnt vmcnt(14)
	v_lshlrev_b32_e32 v15, 16, v42
	s_waitcnt vmcnt(13)
	v_mov_b32_e32 v9, v48
	s_waitcnt vmcnt(12)
	v_mov_b32_e32 v24, v50
	s_waitcnt vmcnt(10)
	v_mov_b32_e32 v25, v58
	v_mov_b32_e32 v78, v58
	v_mov_b32_e32 v79, v50
	v_pk_mul_f32 v[24:25], v[24:25], v[14:15]
	v_pk_mul_f32 v[14:15], v[78:79], v[14:15]
	v_and_b32_e32 v79, 0xffff0000, v42
	v_and_b32_e32 v78, 0xffff0000, v10
	v_mov_b32_e32 v58, v51
	v_mov_b32_e32 v50, v59
	v_pk_mul_f32 v[80:81], v[58:59], v[78:79]
	v_pk_mul_f32 v[50:51], v[50:51], v[78:79]
	v_lshlrev_b32_e32 v59, 16, v43
	v_lshlrev_b32_e32 v58, 16, v11
	v_mov_b32_e32 v78, v52
	v_mov_b32_e32 v79, v60
	v_mov_b32_e32 v82, v60
	v_mov_b32_e32 v83, v52
	v_and_b32_e32 v43, 0xffff0000, v43
	v_and_b32_e32 v42, 0xffff0000, v11
	v_mov_b32_e32 v60, v53
	v_mov_b32_e32 v52, v61
	v_pk_mul_f32 v[78:79], v[78:79], v[58:59]
	v_pk_mul_f32 v[58:59], v[82:83], v[58:59]
	v_pk_mul_f32 v[10:11], v[60:61], v[42:43]
	v_pk_mul_f32 v[42:43], v[52:53], v[42:43]
	v_lshlrev_b32_e32 v53, 16, v44
	v_lshlrev_b32_e32 v52, 16, v12
	v_mov_b32_e32 v60, v46
	v_mov_b32_e32 v61, v54
	v_mov_b32_e32 v82, v54
	v_mov_b32_e32 v83, v46
	v_pk_mul_f32 v[60:61], v[60:61], v[52:53]
	v_pk_mul_f32 v[52:53], v[82:83], v[52:53]
	v_and_b32_e32 v83, 0xffff0000, v44
	v_and_b32_e32 v82, 0xffff0000, v12
	v_mov_b32_e32 v54, v47
	v_pk_mul_f32 v[84:85], v[54:55], v[82:83]
	v_mov_b32_e32 v46, v55
	v_lshlrev_b32_e32 v55, 16, v13
	v_mov_b32_e32 v163, v55
	v_pk_mul_f32 v[46:47], v[46:47], v[82:83]
	v_pk_mul_f32 v[82:83], v[8:9], v[162:163]
	v_sub_f32_e32 v8, v24, v25
	v_mul_f32_e32 v12, v82, v8
	v_add_f32_e32 v8, v15, v14
	v_mul_f32_e32 v14, v82, v8
	v_sub_f32_e32 v8, v80, v81
	v_mul_f32_e32 v15, v82, v8
	v_add_f32_e32 v8, v51, v50
	v_mul_f32_e32 v23, v82, v8
	v_sub_f32_e32 v8, v78, v79
	v_mul_f32_e32 v24, v82, v8
	v_add_f32_e32 v8, v59, v58
	v_mul_f32_e32 v25, v82, v8
	v_sub_f32_e32 v8, v10, v11
	v_mul_f32_e32 v44, v82, v8
	v_add_f32_e32 v8, v43, v42
	v_mul_f32_e32 v42, v82, v8
	v_sub_f32_e32 v8, v60, v61
	v_mul_f32_e32 v43, v82, v8
	v_add_f32_e32 v8, v53, v52
	v_mul_f32_e32 v50, v82, v8
	v_sub_f32_e32 v8, v84, v85
	v_lshlrev_b32_e32 v54, 16, v45
	v_mul_f32_e32 v51, v82, v8
	v_add_f32_e32 v8, v47, v46
	v_mul_f32_e32 v46, v82, v8
	v_fma_f32 v8, -v56, v54, v83
	v_mul_f32_e32 v47, v82, v8
	v_mov_b32_e32 v8, v48
	v_mov_b32_e32 v9, v56
	v_pk_mul_f32 v[8:9], v[8:9], v[54:55]
	v_mov_b32_e32 v56, v49
	v_add_f32_e32 v8, v8, v9
	v_mul_f32_e32 v52, v82, v8
	v_and_b32_e32 v9, 0xffff0000, v45
	v_and_b32_e32 v8, 0xffff0000, v13
	v_pk_mul_f32 v[10:11], v[56:57], v[8:9]
	v_mov_b32_e32 v48, v57
	v_sub_f32_e32 v10, v10, v11
	v_pk_mul_f32 v[8:9], v[48:49], v[8:9]
	v_mul_f32_e32 v11, v82, v10
	v_add_f32_e32 v8, v9, v8
	v_mul_f32_e32 v13, v82, v8
	v_cvt_pk_bf16_f32 v8, v12, v15
	v_cvt_pk_bf16_f32 v9, v24, v44
	v_cvt_pk_bf16_f32 v10, v43, v51
	v_cvt_pk_bf16_f32 v11, v47, v11
	ds_write_b128 v29, v[8:11]
	v_cvt_pk_bf16_f32 v8, v14, v23
	v_cvt_pk_bf16_f32 v9, v25, v42
	v_cvt_pk_bf16_f32 v10, v50, v46
	v_cvt_pk_bf16_f32 v11, v52, v13
	ds_write_b128 v29, v[8:11] offset:128
	s_waitcnt vmcnt(8)
	v_lshlrev_b32_e32 v9, 16, v4
	v_lshlrev_b32_e32 v8, 16, v62
	s_waitcnt vmcnt(6)
	v_mov_b32_e32 v10, v70
	s_waitcnt vmcnt(4)
	v_mov_b32_e32 v11, v74
	v_pk_mul_f32 v[10:11], v[10:11], v[8:9]
	s_nop 0
	v_sub_f32_e32 v10, v10, v11
	v_mul_f32_e32 v12, v82, v10
	v_mov_b32_e32 v10, v74
	v_mov_b32_e32 v11, v70
	v_pk_mul_f32 v[8:9], v[10:11], v[8:9]
	v_mov_b32_e32 v74, v71
	v_add_f32_e32 v8, v9, v8
	v_mul_f32_e32 v13, v82, v8
	v_and_b32_e32 v9, 0xffff0000, v4
	v_and_b32_e32 v8, 0xffff0000, v62
	v_pk_mul_f32 v[10:11], v[74:75], v[8:9]
	v_mov_b32_e32 v70, v75
	v_sub_f32_e32 v4, v10, v11
	v_pk_mul_f32 v[8:9], v[70:71], v[8:9]
	v_mul_f32_e32 v14, v82, v4
	v_add_f32_e32 v4, v9, v8
	v_lshlrev_b32_e32 v9, 16, v5
	v_lshlrev_b32_e32 v8, 16, v63
	v_mov_b32_e32 v10, v72
	v_mov_b32_e32 v11, v76
	v_pk_mul_f32 v[10:11], v[10:11], v[8:9]
	v_mul_f32_e32 v15, v82, v4
	v_sub_f32_e32 v4, v10, v11
	v_mov_b32_e32 v10, v76
	v_mov_b32_e32 v11, v72
	v_pk_mul_f32 v[8:9], v[10:11], v[8:9]
	v_mul_f32_e32 v23, v82, v4
	v_add_f32_e32 v4, v9, v8
	v_mul_f32_e32 v10, v82, v4
	v_and_b32_e32 v5, 0xffff0000, v5
	v_and_b32_e32 v4, 0xffff0000, v63
	v_mov_b32_e32 v76, v73
	v_mov_b32_e32 v72, v77
	v_pk_mul_f32 v[8:9], v[76:77], v[4:5]
	v_pk_mul_f32 v[4:5], v[72:73], v[4:5]
	v_sub_f32_e32 v8, v8, v9
	v_add_f32_e32 v4, v5, v4
	v_mul_f32_e32 v11, v82, v8
	v_mul_f32_e32 v24, v82, v4
	v_lshlrev_b32_e32 v5, 16, v6
	v_lshlrev_b32_e32 v4, 16, v64
	v_mov_b32_e32 v8, v66
	v_mov_b32_e32 v9, v0
	v_pk_mul_f32 v[8:9], v[8:9], v[4:5]
	s_nop 0
	v_sub_f32_e32 v8, v8, v9
	v_mul_f32_e32 v25, v82, v8
	v_mov_b32_e32 v8, v0
	v_mov_b32_e32 v9, v66
	v_pk_mul_f32 v[4:5], v[8:9], v[4:5]
	v_mov_b32_e32 v66, v1
	v_add_f32_e32 v0, v5, v4
	v_mul_f32_e32 v42, v82, v0
	v_and_b32_e32 v5, 0xffff0000, v6
	v_and_b32_e32 v4, 0xffff0000, v64
	v_mov_b32_e32 v0, v67
	v_pk_mul_f32 v[8:9], v[0:1], v[4:5]
	s_nop 0
	v_sub_f32_e32 v0, v8, v9
	v_mul_f32_e32 v6, v82, v0
	v_pk_mul_f32 v[0:1], v[66:67], v[4:5]
	v_mov_b32_e32 v4, v68
	v_add_f32_e32 v0, v1, v0
	v_mul_f32_e32 v8, v82, v0
	v_lshlrev_b32_e32 v1, 16, v7
	v_lshlrev_b32_e32 v0, 16, v65
	v_mov_b32_e32 v5, v2
	v_pk_mul_f32 v[4:5], v[4:5], v[0:1]
	s_nop 0
	v_sub_f32_e32 v4, v4, v5
	v_mul_f32_e32 v9, v82, v4
	v_mov_b32_e32 v4, v2
	v_mov_b32_e32 v5, v68
	v_pk_mul_f32 v[0:1], v[4:5], v[0:1]
	v_mov_b32_e32 v2, v69
	v_add_f32_e32 v0, v1, v0
	v_mul_f32_e32 v43, v82, v0
	v_and_b32_e32 v1, 0xffff0000, v7
	v_and_b32_e32 v0, 0xffff0000, v65
	v_mov_b32_e32 v68, v3
	v_pk_mul_f32 v[4:5], v[2:3], v[0:1]
	v_pk_mul_f32 v[0:1], v[68:69], v[0:1]
	v_sub_f32_e32 v2, v4, v5
	v_add_f32_e32 v0, v1, v0
	v_mul_f32_e32 v5, v82, v0
	v_cvt_pk_bf16_f32 v0, v12, v14
	v_cvt_pk_bf16_f32 v1, v23, v11
	v_mul_f32_e32 v4, v82, v2
	v_cvt_pk_bf16_f32 v2, v25, v6
	v_cvt_pk_bf16_f32 v3, v9, v4
	ds_write_b128 v30, v[0:3]
	v_cvt_pk_bf16_f32 v0, v13, v15
	v_cvt_pk_bf16_f32 v1, v10, v24
	v_mov_b32_e32 v23, v32
	v_cvt_pk_bf16_f32 v2, v42, v8
	v_cvt_pk_bf16_f32 v3, v43, v5
	ds_write_b128 v30, v[0:3] offset:128
	s_waitcnt vmcnt(0)
	ds_write_b128 v37, v[220:223] offset:34816
	ds_write_b128 v38, v[224:227] offset:34816
	ds_write_b128 v39, v[228:231] offset:34816
	ds_write_b128 v40, v[232:235] offset:34816
	s_waitcnt lgkmcnt(0)
	s_barrier
; #define LAS __attribute__((address_space(3)))
; __device__ __forceinline__ unsigned f2bf(float f) { unsigned u = __builtin_bit_cast(unsigned, f); return (u + 0x7fffu + ((u >> 16) & 1u)) >> 16; }
; __device__ __forceinline__ f32x4 mfma16(bf16x8 a, bf16x8 b, f32x4 c) { return __builtin_amdgcn_mfma_f32_16x16x32_bf16(a, b, c, 0, 0, 0); }
; __device__ __forceinline__ bf16x8 cat44(s16x4 lo, s16x4 hi) { return __builtin_shufflevector(lo, hi, 0, 1, 2, 3, 4, 5, 6, 7); }
; __device__ __forceinline__ s16x4 lds_tr(const LAS bf16_t* p) { return __builtin_bit_cast(s16x4, __builtin_amdgcn_ds_read_tr16_b64_v4i16((LAS v4i16_t*)p)); }
; __device__ __forceinline__ void retc1_unit(LAS unsigned char* lds, const bf16_t* proj, const float* cosT, const float* sinT, bf16_t* KVT, int h, int n, int tid) {
;     ...
;     for (int ks = 0; ks < 4; ++ks) { const LAS bf16_t* vp = Vs + (32 * ks + trow) * CP + 16 * w + tcol; af[ks] = cat44(lds_tr(vp), lds_tr(vp + 4 * CP)); }
;     bf16_t* outp = KVT + ((size_t)(h * 128 + n) * 128 + 16 * w + quad * 4) * 128 + l15;
; #pragma unroll
;     for (int dt = 0; dt < 8; ++dt) { f32x4 acc = (f32x4){0.f, 0.f, 0.f, 0.f};
; #pragma unroll
;         for (int ks = 0; ks < 4; ++ks) { const LAS bf16_t* kp = Ks + (32 * ks + trow) * CP + 16 * dt + tcol; const bf16x8 b = cat44(lds_tr(kp), lds_tr(kp + 4 * CP)); acc = mfma16(af[ks], b, acc); }
; #pragma unroll
;         for (int j = 0; j < 4; ++j) outp[(size_t)j * 128 + 16 * dt] = (bf16_t)f2bf(acc[j]); }
	ds_read_b64_tr_b16 v[12:13], v41 offset:34816
	ds_read_b64_tr_b16 v[14:15], v41 offset:35904
	ds_read_b64_tr_b16 v[8:9], v41 offset:43520
	ds_read_b64_tr_b16 v[10:11], v41 offset:44608
	ds_read_b64_tr_b16 v[4:5], v41 offset:52224
	ds_read_b64_tr_b16 v[6:7], v41 offset:53312
	ds_read_b64_tr_b16 v[0:1], v41 offset:60928
	ds_read_b64_tr_b16 v[2:3], v41 offset:62016
	ds_read_b64_tr_b16 v[42:43], v34
	ds_read_b64_tr_b16 v[44:45], v34 offset:1088
	ds_read_b64_tr_b16 v[46:47], v34 offset:8704
	ds_read_b64_tr_b16 v[48:49], v34 offset:9792
	s_lshl_b64 s[10:11], s[8:9], 15
	v_lshl_add_u64 v[24:25], v[20:21], 0, s[10:11]
	v_and_b32_e32 v238, 15, v207
	v_lshrrev_b32_e32 v239, 4, v207
	v_lshlrev_b32_e32 v239, 2, v239
	v_sub_u32_e32 v238, v238, v239
	v_mul_i32_i24_e32 v238, 0xfe, v238
	v_ashrrev_i32_e32 v239, 31, v238
	v_lshl_add_u64 v[240:241], v[24:25], 0, v[238:239]
	s_add_i32 s8, s8, s16
	s_add_i32 s12, s12, s17
	s_mul_i32 s9, s16, 0x3c0000
	v_add_u32_e32 v35, s9, v35
	s_waitcnt lgkmcnt(8)
	ds_read_b64_tr_b16 v[50:51], v34 offset:17408
	ds_read_b64_tr_b16 v[52:53], v34 offset:18496
	ds_read_b64_tr_b16 v[54:55], v34 offset:26112
	ds_read_b64_tr_b16 v[56:57], v34 offset:27200
	s_cmpk_lt_i32 s8, 0x400
	s_waitcnt lgkmcnt(6)
	v_mfma_f32_16x16x32_bf16 v[74:77], v[42:45], v[12:15], 0
	s_waitcnt lgkmcnt(4)
	v_mfma_f32_16x16x32_bf16 v[74:77], v[46:49], v[8:11], v[74:77]
	ds_read_b64_tr_b16 v[58:59], v34 offset:32
	ds_read_b64_tr_b16 v[60:61], v34 offset:1120
	ds_read_b64_tr_b16 v[62:63], v34 offset:8736
	ds_read_b64_tr_b16 v[64:65], v34 offset:9824
	ds_read_b64_tr_b16 v[66:67], v34 offset:17440
	ds_read_b64_tr_b16 v[68:69], v34 offset:18528
	ds_read_b64_tr_b16 v[70:71], v34 offset:26144
	ds_read_b64_tr_b16 v[72:73], v34 offset:27232
	s_waitcnt lgkmcnt(10)
	v_mfma_f32_16x16x32_bf16 v[74:77], v[50:53], v[4:7], v[74:77]
	s_waitcnt lgkmcnt(8)
	v_mfma_f32_16x16x32_bf16 v[74:77], v[54:57], v[0:3], v[74:77]
	s_nop 7
	v_cvt_pk_bf16_f32 v236, v74, v75
	v_cvt_pk_bf16_f32 v237, v76, v77
	global_store_dwordx2 v[240:241], v[236:237], off
	s_waitcnt lgkmcnt(6)
	v_mfma_f32_16x16x32_bf16 v[74:77], v[58:61], v[12:15], 0
	s_waitcnt lgkmcnt(4)
	v_mfma_f32_16x16x32_bf16 v[74:77], v[62:65], v[8:11], v[74:77]
	ds_read_b64_tr_b16 v[42:43], v34 offset:64
	ds_read_b64_tr_b16 v[44:45], v34 offset:1152
	ds_read_b64_tr_b16 v[46:47], v34 offset:8768
	ds_read_b64_tr_b16 v[48:49], v34 offset:9856
	ds_read_b64_tr_b16 v[50:51], v34 offset:17472
	ds_read_b64_tr_b16 v[52:53], v34 offset:18560
	ds_read_b64_tr_b16 v[54:55], v34 offset:26176
	ds_read_b64_tr_b16 v[56:57], v34 offset:27264
	s_waitcnt lgkmcnt(10)
	v_mfma_f32_16x16x32_bf16 v[74:77], v[66:69], v[4:7], v[74:77]
	s_waitcnt lgkmcnt(8)
	v_mfma_f32_16x16x32_bf16 v[74:77], v[70:73], v[0:3], v[74:77]
	s_nop 7
	v_cvt_pk_bf16_f32 v236, v74, v75
	v_cvt_pk_bf16_f32 v237, v76, v77
	global_store_dwordx2 v[240:241], v[236:237], off offset:32
	s_waitcnt lgkmcnt(6)
	v_mfma_f32_16x16x32_bf16 v[74:77], v[42:45], v[12:15], 0
	s_waitcnt lgkmcnt(4)
	v_mfma_f32_16x16x32_bf16 v[74:77], v[46:49], v[8:11], v[74:77]
	ds_read_b64_tr_b16 v[58:59], v34 offset:96
	ds_read_b64_tr_b16 v[60:61], v34 offset:1184
	ds_read_b64_tr_b16 v[62:63], v34 offset:8800
	ds_read_b64_tr_b16 v[64:65], v34 offset:9888
	ds_read_b64_tr_b16 v[66:67], v34 offset:17504
	ds_read_b64_tr_b16 v[68:69], v34 offset:18592
	ds_read_b64_tr_b16 v[70:71], v34 offset:26208
	ds_read_b64_tr_b16 v[72:73], v34 offset:27296
	s_waitcnt lgkmcnt(10)
	v_mfma_f32_16x16x32_bf16 v[74:77], v[50:53], v[4:7], v[74:77]
	s_waitcnt lgkmcnt(8)
	v_mfma_f32_16x16x32_bf16 v[74:77], v[54:57], v[0:3], v[74:77]
	s_nop 7
	v_cvt_pk_bf16_f32 v236, v74, v75
	v_cvt_pk_bf16_f32 v237, v76, v77
	global_store_dwordx2 v[240:241], v[236:237], off offset:64
	s_waitcnt lgkmcnt(6)
	v_mfma_f32_16x16x32_bf16 v[74:77], v[58:61], v[12:15], 0
	s_waitcnt lgkmcnt(4)
; #define LAS __attribute__((address_space(3)))
; __device__ __forceinline__ unsigned f2bf(float f) { unsigned u = __builtin_bit_cast(unsigned, f); return (u + 0x7fffu + ((u >> 16) & 1u)) >> 16; }
; __device__ __forceinline__ void lds_barrier() { asm volatile("s_waitcnt lgkmcnt(0)\n\ts_barrier" ::: "memory"); }
; __device__ __forceinline__ f32x4 mfma16(bf16x8 a, bf16x8 b, f32x4 c) { return __builtin_amdgcn_mfma_f32_16x16x32_bf16(a, b, c, 0, 0, 0); }
; __device__ __forceinline__ bf16x8 cat44(s16x4 lo, s16x4 hi) { return __builtin_shufflevector(lo, hi, 0, 1, 2, 3, 4, 5, 6, 7); }
; __device__ __forceinline__ s16x4 lds_tr(const LAS bf16_t* p) { return __builtin_bit_cast(s16x4, __builtin_amdgcn_ds_read_tr16_b64_v4i16((LAS v4i16_t*)p)); }
; __device__ __forceinline__ void retc1_unit(LAS unsigned char* lds, const bf16_t* proj, const float* cosT, const float* sinT, bf16_t* KVT, int h, int n, int tid) {
;     ...
;     for (int dt = 0; dt < 8; ++dt) { f32x4 acc = (f32x4){0.f, 0.f, 0.f, 0.f};
; #pragma unroll
;         for (int ks = 0; ks < 4; ++ks) { const LAS bf16_t* kp = Ks + (32 * ks + trow) * CP + 16 * dt + tcol; const bf16x8 b = cat44(lds_tr(kp), lds_tr(kp + 4 * CP)); acc = mfma16(af[ks], b, acc); }
; #pragma unroll
;         for (int j = 0; j < 4; ++j) outp[(size_t)j * 128 + 16 * dt] = (bf16_t)f2bf(acc[j]); }
;     lds_barrier();
	v_mfma_f32_16x16x32_bf16 v[74:77], v[62:65], v[8:11], v[74:77]
	ds_read_b64_tr_b16 v[42:43], v34 offset:128
	ds_read_b64_tr_b16 v[44:45], v34 offset:1216
	ds_read_b64_tr_b16 v[46:47], v34 offset:8832
	ds_read_b64_tr_b16 v[48:49], v34 offset:9920
	ds_read_b64_tr_b16 v[50:51], v34 offset:17536
	ds_read_b64_tr_b16 v[52:53], v34 offset:18624
	ds_read_b64_tr_b16 v[54:55], v34 offset:26240
	ds_read_b64_tr_b16 v[56:57], v34 offset:27328
	s_waitcnt lgkmcnt(10)
	v_mfma_f32_16x16x32_bf16 v[74:77], v[66:69], v[4:7], v[74:77]
	s_waitcnt lgkmcnt(8)
	v_mfma_f32_16x16x32_bf16 v[74:77], v[70:73], v[0:3], v[74:77]
	s_nop 7
	v_cvt_pk_bf16_f32 v236, v74, v75
	v_cvt_pk_bf16_f32 v237, v76, v77
	global_store_dwordx2 v[240:241], v[236:237], off offset:96
	s_waitcnt lgkmcnt(6)
	v_mfma_f32_16x16x32_bf16 v[74:77], v[42:45], v[12:15], 0
	s_waitcnt lgkmcnt(4)
	v_mfma_f32_16x16x32_bf16 v[74:77], v[46:49], v[8:11], v[74:77]
	ds_read_b64_tr_b16 v[58:59], v34 offset:160
	ds_read_b64_tr_b16 v[60:61], v34 offset:1248
	ds_read_b64_tr_b16 v[62:63], v34 offset:8864
	ds_read_b64_tr_b16 v[64:65], v34 offset:9952
	ds_read_b64_tr_b16 v[66:67], v34 offset:17568
	ds_read_b64_tr_b16 v[68:69], v34 offset:18656
	ds_read_b64_tr_b16 v[70:71], v34 offset:26272
	ds_read_b64_tr_b16 v[72:73], v34 offset:27360
	s_waitcnt lgkmcnt(10)
	v_mfma_f32_16x16x32_bf16 v[74:77], v[50:53], v[4:7], v[74:77]
	s_waitcnt lgkmcnt(8)
	v_mfma_f32_16x16x32_bf16 v[74:77], v[54:57], v[0:3], v[74:77]
	s_nop 7
	v_cvt_pk_bf16_f32 v236, v74, v75
	v_cvt_pk_bf16_f32 v237, v76, v77
	global_store_dwordx2 v[240:241], v[236:237], off offset:128
	s_waitcnt lgkmcnt(6)
	v_mfma_f32_16x16x32_bf16 v[74:77], v[58:61], v[12:15], 0
	s_waitcnt lgkmcnt(4)
	v_mfma_f32_16x16x32_bf16 v[74:77], v[62:65], v[8:11], v[74:77]
	ds_read_b64_tr_b16 v[42:43], v34 offset:192
	ds_read_b64_tr_b16 v[44:45], v34 offset:1280
	ds_read_b64_tr_b16 v[46:47], v34 offset:8896
	ds_read_b64_tr_b16 v[48:49], v34 offset:9984
	ds_read_b64_tr_b16 v[50:51], v34 offset:17600
	ds_read_b64_tr_b16 v[52:53], v34 offset:18688
	ds_read_b64_tr_b16 v[54:55], v34 offset:26304
	ds_read_b64_tr_b16 v[56:57], v34 offset:27392
	s_waitcnt lgkmcnt(10)
	v_mfma_f32_16x16x32_bf16 v[74:77], v[66:69], v[4:7], v[74:77]
	s_waitcnt lgkmcnt(8)
	v_mfma_f32_16x16x32_bf16 v[74:77], v[70:73], v[0:3], v[74:77]
	s_nop 7
	v_cvt_pk_bf16_f32 v236, v74, v75
	v_cvt_pk_bf16_f32 v237, v76, v77
	global_store_dwordx2 v[240:241], v[236:237], off offset:160
	s_waitcnt lgkmcnt(6)
	v_mfma_f32_16x16x32_bf16 v[74:77], v[42:45], v[12:15], 0
	s_waitcnt lgkmcnt(4)
	v_mfma_f32_16x16x32_bf16 v[74:77], v[46:49], v[8:11], v[74:77]
	ds_read_b64_tr_b16 v[58:59], v34 offset:224
	ds_read_b64_tr_b16 v[60:61], v34 offset:1312
	ds_read_b64_tr_b16 v[62:63], v34 offset:8928
	ds_read_b64_tr_b16 v[64:65], v34 offset:10016
	ds_read_b64_tr_b16 v[66:67], v34 offset:17632
	ds_read_b64_tr_b16 v[68:69], v34 offset:18720
	ds_read_b64_tr_b16 v[70:71], v34 offset:26336
	ds_read_b64_tr_b16 v[72:73], v34 offset:27424
	s_waitcnt lgkmcnt(10)
	v_mfma_f32_16x16x32_bf16 v[74:77], v[50:53], v[4:7], v[74:77]
	s_waitcnt lgkmcnt(8)
	v_mfma_f32_16x16x32_bf16 v[74:77], v[54:57], v[0:3], v[74:77]
	s_nop 7
	v_cvt_pk_bf16_f32 v236, v74, v75
	v_cvt_pk_bf16_f32 v237, v76, v77
	global_store_dwordx2 v[240:241], v[236:237], off offset:192
	s_waitcnt lgkmcnt(6)
	v_mfma_f32_16x16x32_bf16 v[74:77], v[58:61], v[12:15], 0
	s_waitcnt lgkmcnt(4)
	v_mfma_f32_16x16x32_bf16 v[74:77], v[62:65], v[8:11], v[74:77]
	s_waitcnt lgkmcnt(2)
	v_mfma_f32_16x16x32_bf16 v[74:77], v[66:69], v[4:7], v[74:77]
	s_waitcnt lgkmcnt(0)
	v_mfma_f32_16x16x32_bf16 v[74:77], v[70:73], v[0:3], v[74:77]
	s_nop 7
	v_cvt_pk_bf16_f32 v236, v74, v75
	v_cvt_pk_bf16_f32 v237, v76, v77
	global_store_dwordx2 v[240:241], v[236:237], off offset:224
	s_waitcnt lgkmcnt(0)
	s_barrier
	s_cbranch_scc1 .LBB0_278
